# ret_out prologue loads hoisted + jt-loop V reads batched; sg_ple reads regrouped; acc zero-init via v_mov_b64; on top of v17
# speedup vs baseline: 1.0171x; 1.0069x over previous
; DEV int tidx() { int t = threadIdx.x; asm volatile("" : "+v"(t)); return t; }
; DEV float log_gamma(int h) { return log1pf(-exp2f(-5.0f - (float)h)); }
; DEV void ret_out_item(const Params& p, int l, int item, unsigned char* smem) {
;     ...
;   const int tid = tidx(), lane = tid & 63, w = tid >> 6, fr = lane & 15, fq = lane >> 4;
;   const size_t rowbase = (size_t)b * SEQ + n * 128;
;   const float lg = log_gamma(h);
;   {
;     u32x4 q[2], k[2], v[4], g[4];
; #pragma unroll
;     for (int i = 0; i < 2; ++i) {
;       const int c = tid + i * 512, r = c >> 3, kc = c & 7;
;       q[i] = *(const u32x4*)(Z + (rowbase + r) * NIN + RQ + h * 64 + kc * 8);
;       k[i] = *(const u32x4*)(Z + (rowbase + r) * NIN + RK + h * 64 + kc * 8);
;     }
.LBB0_85:
	s_ashr_i32 s0, s18, 7
	s_ashr_i32 s1, s0, 31
	s_bfe_u32 s4, s18, 0x20005
	s_lshl_b64 s[38:39], s[0:1], 12
	s_lshl_b32 s0, s18, 7
	s_and_b32 s0, s0, 0xf80
	v_cvt_f32_ubyte0_e32 v0, s4
	s_or_b32 s38, s38, s0
	v_sub_f32_e32 v0, 0xc0a00000, v0
	s_mov_b32 s0, 0xc2fc0000
	v_cmp_gt_f32_e32 vcc, s0, v0
	s_ashr_i32 s19, s18, 31
	s_lshl_b64 s[2:3], s[18:19], 14
	s_waitcnt lgkmcnt(0)
	v_cndmask_b32_e32 v1, 0, v203, vcc
	v_add_f32_e32 v0, v0, v1
	v_exp_f32_e32 v0, v0
	s_and_b64 s[0:1], vcc, exec
	s_cselect_b32 s0, 0xffffffc0, 0
	v_mov_b32_e32 v44, v171
	v_ldexp_f32 v33, v0, s0
	v_sub_f32_e32 v2, 1.0, v33
	v_add_f32_e32 v0, -1.0, v2
	v_sub_f32_e32 v1, v0, v2
	v_add_f32_e32 v1, 1.0, v1
	v_sub_f32_e64 v0, -v33, v0
	v_add_f32_e32 v3, v0, v1
	v_frexp_mant_f32_e32 v0, v2
	s_mov_b32 s0, 0x3f2aaaab
	v_cmp_gt_f32_e32 vcc, s0, v0
	v_cvt_f64_f32_e32 v[0:1], v2
	v_frexp_exp_i32_f64_e32 v0, v[0:1]
	v_subbrev_co_u32_e32 v0, vcc, 0, v0, vcc
	v_sub_u32_e32 v1, 0, v0
	v_ldexp_f32 v2, v2, v1
	v_ldexp_f32 v1, v3, v1
	v_add_f32_e32 v3, -1.0, v2
	v_add_f32_e32 v4, 1.0, v3
	v_sub_f32_e32 v4, v2, v4
	v_add_f32_e32 v4, v1, v4
	v_add_f32_e32 v5, v3, v4
	v_sub_f32_e32 v3, v5, v3
	v_sub_f32_e32 v3, v4, v3
	v_add_f32_e32 v4, 1.0, v2
	v_add_f32_e32 v6, -1.0, v4
	v_sub_f32_e32 v2, v2, v6
	v_add_f32_e32 v1, v1, v2
	v_add_f32_e32 v2, v4, v1
	v_sub_f32_e32 v4, v2, v4
	v_sub_f32_e32 v1, v1, v4
	v_rcp_f32_e32 v4, v2
	v_cvt_f32_i32_e32 v0, v0
	s_mov_b32 s0, 0x3f317218
	v_mul_f32_e32 v6, v5, v4
	v_mul_f32_e32 v7, v2, v6
	v_fma_f32 v8, v6, v2, -v7
	v_fmac_f32_e32 v8, v6, v1
	v_add_f32_e32 v9, v7, v8
	v_sub_f32_e32 v10, v5, v9
	v_sub_f32_e32 v5, v5, v10
	v_sub_f32_e32 v7, v9, v7
	v_sub_f32_e32 v5, v5, v9
	v_add_f32_e32 v3, v3, v5
	v_sub_f32_e32 v5, v7, v8
	v_add_f32_e32 v3, v5, v3
	v_add_f32_e32 v5, v10, v3
	v_mul_f32_e32 v7, v4, v5
	v_mul_f32_e32 v8, v2, v7
	v_fma_f32 v2, v7, v2, -v8
	v_fmac_f32_e32 v2, v7, v1
	v_sub_f32_e32 v1, v10, v5
	v_add_f32_e32 v1, v3, v1
	v_add_f32_e32 v3, v8, v2
	v_sub_f32_e32 v9, v5, v3
	v_sub_f32_e32 v5, v5, v9
	v_sub_f32_e32 v8, v3, v8
	v_sub_f32_e32 v3, v5, v3
	v_add_f32_e32 v1, v1, v3
	v_sub_f32_e32 v2, v8, v2
	v_add_f32_e32 v1, v2, v1
	v_add_f32_e32 v2, v6, v7
	v_add_f32_e32 v1, v9, v1
	v_sub_f32_e32 v3, v2, v6
	v_mul_f32_e32 v1, v4, v1
	v_sub_f32_e32 v3, v7, v3
	v_add_f32_e32 v1, v3, v1
	v_mul_f32_e32 v6, 0x3f317218, v0
	v_add_f32_e32 v3, v2, v1
	v_fma_f32 v7, v0, s0, -v6
	v_mul_f32_e32 v4, v3, v3
	v_fmac_f32_e32 v7, 0xb102e308, v0
	v_sub_f32_e32 v0, v3, v2
	v_fmamk_f32 v5, v4, 0x3e9b6dac, v201
	v_sub_f32_e32 v0, v1, v0
	v_add_f32_e32 v1, v6, v7
	v_fmaak_f32 v5, v4, v5, 0x3f2aaada
	v_sub_f32_e32 v2, v1, v6
	v_ldexp_f32 v6, v3, 1
	v_mul_f32_e32 v3, v3, v4
	v_mul_f32_e32 v3, v3, v5
	v_add_f32_e32 v4, v6, v3
	v_sub_f32_e32 v5, v4, v6
	v_ldexp_f32 v0, v0, 1
	v_sub_f32_e32 v3, v3, v5
	v_add_f32_e32 v0, v0, v3
	v_add_f32_e32 v3, v4, v0
	v_sub_f32_e32 v4, v3, v4
	v_sub_f32_e32 v0, v0, v4
	v_add_f32_e32 v4, v1, v3
	v_sub_f32_e32 v5, v4, v1
	v_sub_f32_e32 v6, v4, v5
	v_sub_f32_e32 v2, v7, v2
	v_sub_f32_e32 v1, v1, v6
	v_sub_f32_e32 v3, v3, v5
	v_add_f32_e32 v1, v3, v1
	v_add_f32_e32 v3, v2, v0
	v_sub_f32_e32 v5, v3, v2
	v_sub_f32_e32 v6, v3, v5
	v_add_f32_e32 v1, v3, v1
	v_sub_f32_e32 v2, v2, v6
	v_sub_f32_e32 v0, v0, v5
	v_add_f32_e32 v5, v4, v1
	v_add_f32_e32 v0, v0, v2
	v_sub_f32_e32 v2, v5, v4
	v_ashrrev_i32_e32 v16, 3, v44
	v_sub_f32_e32 v1, v1, v2
	v_ashrrev_i32_e32 v17, 31, v16
	v_add_f32_e32 v4, v0, v1
	s_mov_b32 s0, 0x33800000
	v_lshl_add_u64 v[0:1], s[38:39], 0, v[16:17]
	v_mov_b64_e32 v[12:13], s[30:31]
	v_cmp_gt_f32_e32 vcc, s0, v33
	v_mad_u64_u32 v[2:3], s[0:1], v0, s95, v[12:13]
	v_mad_i32_i24 v3, v1, s95, v3
	s_lshl_b32 s6, s4, 7
	v_lshl_add_u64 v[0:1], v[2:3], 0, s[6:7]
	v_lshlrev_b32_e32 v2, 4, v44
	v_add_u32_e32 v7, 0x200, v44
	v_and_b32_e32 v168, 0x70, v2
	v_ashrrev_i32_e32 v18, 3, v7
	v_lshl_add_u64 v[0:1], v[0:1], 0, v[168:169]
	v_ashrrev_i32_e32 v19, 31, v18
	global_load_dwordx4 v[48:51], v[0:1], off
	global_load_dwordx4 v[52:55], v[0:1], off offset:512
	v_lshl_add_u64 v[0:1], s[38:39], 0, v[18:19]
	v_mad_u64_u32 v[2:3], s[0:1], v0, s95, v[12:13]
	v_mad_i32_i24 v3, v1, s95, v3
	v_lshl_add_u64 v[0:1], v[2:3], 0, s[6:7]
	v_lshl_add_u64 v[0:1], v[0:1], 0, v[168:169]
	global_load_dwordx4 v[56:59], v[0:1], off
	global_load_dwordx4 v[60:63], v[0:1], off offset:512
	v_add_f32_e32 v0, v5, v4
	v_cmp_nlt_f32_e64 s[0:1], 1.0, v33
	v_and_b32_e32 v32, 0x7f, v44
	v_add_u32_e32 v8, 0x400, v44
	v_cndmask_b32_e64 v0, v204, v0, s[0:1]
	v_cmp_neq_f32_e64 s[0:1], 1.0, v33
	v_add_u32_e32 v17, 0x600, v44
	v_ashrrev_i32_e32 v40, 4, v44
	v_cndmask_b32_e64 v46, v205, v0, s[0:1]
	v_or_b32_e32 v0, s38, v32
	v_mad_u64_u32 v[0:1], s[0:1], v0, s95, v[12:13]
	v_ashrrev_i32_e32 v20, 4, v7
	v_ashrrev_i32_e32 v22, 4, v8
	v_ashrrev_i32_e32 v24, 4, v17
	v_lshlrev_b32_e32 v6, 3, v44
	v_mad_i32_i24 v1, s39, v206, v1
	s_lshl_b32 s0, s4, 8
	s_mov_b32 s1, s7
	v_and_b32_e32 v64, -8, v40
	v_and_b32_e32 v26, -8, v20
	v_and_b32_e32 v28, -8, v22
	v_and_b32_e32 v30, -8, v24
	v_lshl_add_u64 v[14:15], v[0:1], 0, s[0:1]
	v_and_b32_e32 v4, 0x78, v6
	v_ashrrev_i32_e32 v65, 31, v64
	v_ashrrev_i32_e32 v41, 31, v40
	v_ashrrev_i32_e32 v27, 31, v26
	v_ashrrev_i32_e32 v21, 31, v20
	v_ashrrev_i32_e32 v29, 31, v28
	v_ashrrev_i32_e32 v23, 31, v22
	v_ashrrev_i32_e32 v31, 31, v30
	v_ashrrev_i32_e32 v25, 31, v24
	v_lshl_add_u64 v[42:43], v[64:65], 1, v[14:15]
	v_lshl_add_u64 v[0:1], s[38:39], 0, v[40:41]
	v_lshlrev_b32_e32 v76, 1, v4
	v_lshl_add_u64 v[38:39], v[26:27], 1, v[14:15]
	v_lshl_add_u64 v[4:5], s[38:39], 0, v[20:21]
	v_lshl_add_u64 v[36:37], v[28:29], 1, v[14:15]
; DEV void ret_out_item(const Params& p, int l, int item, unsigned char* smem) {
;     ...
; #pragma unroll
;     for (int i = 0; i < 4; ++i) {
;       const int c = tid + i * 512;
;       v[i] = *(const u32x4*)(Z + (rowbase + (c & 127)) * NIN + RV + h * 128 + (c >> 7) * 8);
;       g[i] = *(const u32x4*)(Z + (rowbase + (c >> 4)) * NIN + RG + h * 128 + (c & 15) * 8);
;     }
; #pragma unroll
;     for (int i = 0; i < 2; ++i) {
;       const int c = tid + i * 512, r = c >> 3, kc = c & 7;
;       *(u32x4*)(Qs + r * 144 + kc * 16) = q[i];
;       *(u32x4*)(Ks + r * 144 + kc * 16) = k[i];
;     }
; #pragma unroll
;     for (int i = 0; i < 4; ++i) {
;       const int c = tid + i * 512, r = c & 127, kc = c >> 7;
;       bf16_t* dst = Vt + (kc * 8) * 136 + r;
;       dst[0 * 136] = (bf16_t)(v[i].x & 0xffff); dst[1 * 136] = (bf16_t)(v[i].x >> 16);
;       dst[2 * 136] = (bf16_t)(v[i].y & 0xffff); dst[3 * 136] = (bf16_t)(v[i].y >> 16);
;       dst[4 * 136] = (bf16_t)(v[i].z & 0xffff); dst[5 * 136] = (bf16_t)(v[i].z >> 16);
;       dst[6 * 136] = (bf16_t)(v[i].w & 0xffff); dst[7 * 136] = (bf16_t)(v[i].w >> 16);
;       *(u32x4*)(Gs + (c >> 4) * 136 + (c & 15) * 8) = g[i];
;     }
; #pragma unroll
;     for (int i = 0; i < 2; ++i) {
;       const int c = tid + i * 512, r = c >> 3, kc = c & 7;
;       *(u32x4*)(smem + 106496 + r * 144 + kc * 16) = *(const u32x4*)(Sb + r * 64 + kc * 8);
;     }
;   }
;   __syncthreads();
	v_lshl_add_u64 v[8:9], s[38:39], 0, v[22:23]
	v_lshl_add_u64 v[34:35], v[30:31], 1, v[14:15]
	v_lshl_add_u64 v[14:15], s[38:39], 0, v[24:25]
	v_mad_u64_u32 v[2:3], s[4:5], v0, s95, v[12:13]
	v_mad_u64_u32 v[6:7], s[4:5], v4, s95, v[12:13]
	v_mad_u64_u32 v[10:11], s[4:5], v8, s95, v[12:13]
	v_mad_u64_u32 v[12:13], s[4:5], v14, s95, v[12:13]
	v_mad_i32_i24 v3, v1, s95, v3
	v_mad_i32_i24 v7, v5, s95, v7
	v_mad_i32_i24 v11, v9, s95, v11
	v_mad_i32_i24 v13, v15, s95, v13
	v_lshl_add_u64 v[0:1], v[2:3], 0, s[0:1]
	v_mov_b32_e32 v77, v169
	v_lshl_add_u64 v[4:5], v[6:7], 0, s[0:1]
	v_lshl_add_u64 v[8:9], v[10:11], 0, s[0:1]
	v_lshl_add_u64 v[12:13], v[12:13], 0, s[0:1]
	v_add_u32_e32 v21, 0, v168
	v_mul_lo_u32 v19, v16, s33
	v_lshl_add_u64 v[0:1], v[0:1], 0, v[76:77]
	v_lshl_add_u64 v[4:5], v[4:5], 0, v[76:77]
	v_lshl_add_u64 v[8:9], v[8:9], 0, v[76:77]
	v_lshl_add_u64 v[12:13], v[12:13], 0, v[76:77]
	v_add_u32_e32 v17, v21, v19
	global_load_dwordx4 v[0:3], v[0:1], off offset:2048
	s_add_u32 s0, s8, s2
	global_load_dwordx4 v[4:7], v[4:5], off offset:2048
	v_lshl_add_u32 v32, v32, 1, 0
	global_load_dwordx4 v[8:11], v[8:9], off offset:2048
	s_addc_u32 s1, s9, s3
	global_load_dwordx4 v[12:15], v[12:13], off offset:2048
	global_load_dwordx4 v[96:99], v[42:43], off offset:1024
	global_load_dwordx4 v[100:103], v[38:39], off offset:1024
	global_load_dwordx4 v[104:107], v[36:37], off offset:1024
	global_load_dwordx4 v[108:111], v[34:35], off offset:1024
	v_lshlrev_b32_e32 v112, 6, v16
	v_lshl_add_u64 v[114:115], s[0:1], 0, v[168:169]
	v_ashrrev_i32_e32 v113, 31, v112
	v_lshlrev_b32_e32 v120, 6, v18
	v_lshl_add_u64 v[112:113], v[112:113], 1, v[114:115]
	v_ashrrev_i32_e32 v121, 31, v120
	global_load_dwordx4 v[116:119], v[112:113], off
	v_lshl_add_u64 v[120:121], v[120:121], 1, v[114:115]
	global_load_dwordx4 v[124:127], v[120:121], off
	s_waitcnt vmcnt(13)
	ds_write_b128 v17, v[48:51]
	s_waitcnt vmcnt(12)
	ds_write_b128 v17, v[52:55] offset:18432
	v_mul_lo_u32 v17, v18, s33
	v_add_u32_e32 v21, v21, v17
	s_waitcnt vmcnt(11)
	ds_write_b128 v21, v[56:59]
	s_waitcnt vmcnt(10)
	ds_write_b128 v21, v[60:63] offset:18432
	v_mad_u64_u32 v[52:53], s[2:3], v64, s13, v[32:33]
	v_bfe_u32 v79, v44, 4, 2
	v_add_u32_e32 v78, s12, v76
	v_mad_u64_u32 v[42:43], s[2:3], v40, s13, v[78:79]
	v_ashrrev_i32_e32 v45, 6, v44
	v_and_b32_e32 v81, 15, v44
	v_lshlrev_b32_e32 v80, 4, v45
	v_or_b32_e32 v82, v80, v81
	s_movk_i32 s4, 0x110
	v_cndmask_b32_e64 v90, v46, -v33, vcc
	v_cmp_lt_i32_e32 vcc, -1, v45
	v_lshlrev_b32_e32 v83, 2, v79
	s_waitcnt vmcnt(5)
	ds_write_b16 v52, v96 offset:36864
	ds_write_b16_d16_hi v52, v96 offset:37136
	ds_write_b16 v52, v97 offset:37408
	ds_write_b16_d16_hi v52, v97 offset:37680
	ds_write_b16 v52, v98 offset:37952
	ds_write_b16_d16_hi v52, v98 offset:38224
	ds_write_b16 v52, v99 offset:38496
	ds_write_b16_d16_hi v52, v99 offset:38768
	ds_write_b128 v42, v[0:3]
	v_mad_u64_u32 v[0:1], s[2:3], v26, s13, v[32:33]
	s_waitcnt vmcnt(4)
	ds_write_b16 v0, v100 offset:36864
	ds_write_b16_d16_hi v0, v100 offset:37136
	ds_write_b16 v0, v101 offset:37408
	ds_write_b16_d16_hi v0, v101 offset:37680
	ds_write_b16 v0, v102 offset:37952
	ds_write_b16_d16_hi v0, v102 offset:38224
	ds_write_b16 v0, v103 offset:38496
	ds_write_b16_d16_hi v0, v103 offset:38768
	v_mad_u64_u32 v[0:1], s[2:3], v20, s13, v[78:79]
	ds_write_b128 v0, v[4:7]
	v_mad_u64_u32 v[0:1], s[2:3], v28, s13, v[32:33]
	s_waitcnt vmcnt(3)
	ds_write_b16 v0, v104 offset:36864
	ds_write_b16_d16_hi v0, v104 offset:37136
	ds_write_b16 v0, v105 offset:37408
	ds_write_b16_d16_hi v0, v105 offset:37680
	ds_write_b16 v0, v106 offset:37952
	ds_write_b16_d16_hi v0, v106 offset:38224
	ds_write_b16 v0, v107 offset:38496
	ds_write_b16_d16_hi v0, v107 offset:38768
	v_mad_u64_u32 v[0:1], s[2:3], v22, s13, v[78:79]
	ds_write_b128 v0, v[8:11]
	v_mad_u64_u32 v[0:1], s[2:3], v30, s13, v[32:33]
	s_waitcnt vmcnt(2)
	ds_write_b16 v0, v108 offset:36864
	ds_write_b16_d16_hi v0, v108 offset:37136
	ds_write_b16 v0, v109 offset:37408
	ds_write_b16_d16_hi v0, v109 offset:37680
	ds_write_b16 v0, v110 offset:37952
	ds_write_b16_d16_hi v0, v110 offset:38224
	ds_write_b16 v0, v111 offset:38496
	ds_write_b16_d16_hi v0, v111 offset:38768
	v_mad_u64_u32 v[0:1], s[2:3], v24, s13, v[78:79]
	ds_write_b128 v0, v[12:15]
	v_readlane_b32 s0, v248, 16
	v_and_b32_e32 v32, 48, v44
	v_mul_u32_u24_e32 v34, 0x90, v81
	v_add_u32_e32 v6, s0, v168
	v_add_u32_e32 v7, v6, v19
	v_add3_u32 v35, s0, v32, v34
	s_waitcnt vmcnt(1)
	ds_write_b128 v7, v[116:119]
	v_add_u32_e32 v4, v6, v17
	s_waitcnt vmcnt(0)
	ds_write_b128 v4, v[124:127]
	v_mul_lo_u32 v0, v82, s33
	v_add3_u32 v0, 0, v0, v32
	s_waitcnt lgkmcnt(0)
	s_barrier
; DEV f32x4 mfma32(bf16x8 a, bf16x8 b, f32x4 c) { return __builtin_amdgcn_mfma_f32_16x16x32_bf16(a, b, c, 0, 0, 0); }
; DEV f32x4 mfma16(bf16x4 a, bf16x4 b, f32x4 c) { return __builtin_amdgcn_mfma_f32_16x16x16bf16_1k(a, b, c, 0, 0, 0); }
; DEV void ret_out_item(const Params& p, int l, int item, unsigned char* smem) {
;     ...
;   bf16x8 qf[2];
; #pragma unroll
;   for (int ks = 0; ks < 2; ++ks) qf[ks] = *(const bf16x8*)(Qs + (w * 16 + fr) * 144 + ks * 64 + fq * 16);
;   f32x4 a1[8], a2[8];
; #pragma unroll
;   for (int et = 0; et < 8; ++et) {
;     a1[et] = (f32x4){0.f, 0.f, 0.f, 0.f};
;     a2[et] = (f32x4){0.f, 0.f, 0.f, 0.f};
; #pragma unroll
;     for (int ks = 0; ks < 2; ++ks) {
;       const bf16x8 sf = *(const bf16x8*)(smem + 106496 + (et * 16 + fr) * 144 + ks * 64 + fq * 16);
;       a2[et] = mfma32(qf[ks], sf, a2[et]);
;     }
;   }
;   const int qi = w * 16 + fr;
;   for (int jt = 0; jt <= w; ++jt) {
;     f32x4 s = (f32x4){0.f, 0.f, 0.f, 0.f};
; #pragma unroll
;     for (int ks = 0; ks < 2; ++ks) {
;       const bf16x8 kf = *(const bf16x8*)(Ks + (jt * 16 + fr) * 144 + ks * 64 + fq * 16);
;       s = mfma32(kf, qf[ks], s);
;     }
;     float pv[4];
; #pragma unroll
;     for (int jj = 0; jj < 4; ++jj) {
;       const int kj = jt * 16 + fq * 4 + jj;
;       pv[jj] = (qi >= kj) ? s[jj] * 0.125f * __expf(lg * (float)(qi - kj)) : 0.f;
;     }
;     const bf16x4 pf = pack4(pv[0], pv[1], pv[2], pv[3]);
; #pragma unroll
;     for (int et = 0; et < 8; ++et) {
;       const bf16x4 vf = *(const bf16x4*)(Vt + (et * 16 + fr) * 136 + jt * 16 + fq * 4);
;       a1[et] = mfma16(pf, vf, a1[et]);
;     }
;   }
	ds_read_b128 v[64:67], v0
	ds_read_b128 v[68:71], v0 offset:64
	ds_read_b128 v[0:3], v35
	ds_read_b128 v[4:7], v35 offset:64
	s_waitcnt lgkmcnt(1)
	v_mfma_f32_16x16x32_bf16 v[0:3], v[64:67], v[0:3], 0
	ds_read_b128 v[8:11], v35 offset:2368
	ds_read_b128 v[12:15], v35 offset:4672
	ds_read_b128 v[16:19], v35 offset:6976
	s_waitcnt lgkmcnt(3)
	v_mfma_f32_16x16x32_bf16 v[0:3], v[68:71], v[4:7], v[0:3]
	ds_read_b128 v[4:7], v35 offset:2304
	ds_read_b128 v[20:23], v35 offset:9280
	ds_read_b128 v[24:27], v35 offset:11584
	s_waitcnt lgkmcnt(2)
	v_mfma_f32_16x16x32_bf16 v[4:7], v[64:67], v[4:7], 0
	ds_read_b128 v[28:31], v35 offset:13888
	ds_read_b128 v[36:39], v35 offset:16192
	v_mfma_f32_16x16x32_bf16 v[4:7], v[68:71], v[8:11], v[4:7]
	ds_read_b128 v[8:11], v35 offset:4608
	s_waitcnt lgkmcnt(0)
	v_mfma_f32_16x16x32_bf16 v[8:11], v[64:67], v[8:11], 0
	v_mfma_f32_16x16x32_bf16 v[8:11], v[68:71], v[12:15], v[8:11]
	ds_read_b128 v[12:15], v35 offset:6912
	s_waitcnt lgkmcnt(0)
	v_mfma_f32_16x16x32_bf16 v[12:15], v[64:67], v[12:15], 0
	v_mfma_f32_16x16x32_bf16 v[12:15], v[68:71], v[16:19], v[12:15]
	ds_read_b128 v[16:19], v35 offset:9216
	s_waitcnt lgkmcnt(0)
	v_mfma_f32_16x16x32_bf16 v[16:19], v[64:67], v[16:19], 0
	v_mfma_f32_16x16x32_bf16 v[16:19], v[68:71], v[20:23], v[16:19]
	ds_read_b128 v[20:23], v35 offset:11520
	s_waitcnt lgkmcnt(0)
	v_mfma_f32_16x16x32_bf16 v[20:23], v[64:67], v[20:23], 0
	v_mfma_f32_16x16x32_bf16 v[20:23], v[68:71], v[24:27], v[20:23]
	ds_read_b128 v[24:27], v35 offset:13824
	s_waitcnt lgkmcnt(0)
	v_mfma_f32_16x16x32_bf16 v[24:27], v[64:67], v[24:27], 0
	v_mfma_f32_16x16x32_bf16 v[24:27], v[68:71], v[28:31], v[24:27]
	ds_read_b128 v[28:31], v35 offset:16128
	s_waitcnt lgkmcnt(0)
	v_mfma_f32_16x16x32_bf16 v[28:31], v[64:67], v[28:31], 0
	v_mfma_f32_16x16x32_bf16 v[28:31], v[68:71], v[36:39], v[28:31]
	s_and_saveexec_b64 s[0:1], vcc
	s_xor_b64 s[0:1], exec, s[0:1]
	s_cbranch_execz .LBB0_91
	s_movk_i32 s2, 0x4800
	v_lshlrev_b32_e32 v83, 2, v79
	v_add3_u32 v86, v34, v32, s2
	v_add_u32_e32 v32, v80, v81
	v_lshlrev_b32_e32 v33, 3, v79
	v_sub_u32_e32 v87, v32, v83
	v_mov_b32_e32 v32, 0
	v_mov_b32_e32 v77, v82
	v_add_u32_e32 v84, 1, v45
	v_mad_u32_u24 v85, v81, s4, v33
	s_mov_b64 s[2:3], 0
	v_mov_b32_e32 v88, v83
	v_mov_b32_e32 v33, v32
	v_mov_b32_e32 v34, v32
	v_mov_b32_e32 v35, v32
	v_mov_b32_e32 v36, v32
	v_mov_b32_e32 v37, v32
	v_mov_b32_e32 v38, v32
	v_mov_b32_e32 v39, v32
	v_mov_b32_e32 v56, v32
	v_mov_b32_e32 v57, v32
	v_mov_b32_e32 v58, v32
	v_mov_b32_e32 v59, v32
	v_mov_b32_e32 v60, v32
	v_mov_b32_e32 v61, v32
	v_mov_b32_e32 v62, v32
	v_mov_b32_e32 v63, v32
	v_mov_b32_e32 v40, v32
	v_mov_b32_e32 v41, v32
	v_mov_b32_e32 v42, v32
	v_mov_b32_e32 v43, v32
	v_mov_b32_e32 v48, v32
	v_mov_b32_e32 v49, v32
	v_mov_b32_e32 v50, v32
	v_mov_b32_e32 v51, v32
	v_mov_b32_e32 v44, v32
	v_mov_b32_e32 v45, v32
	v_mov_b32_e32 v46, v32
	v_mov_b32_e32 v47, v32
	v_mov_b32_e32 v52, v32
	v_mov_b32_e32 v53, v32
	v_mov_b32_e32 v54, v32
	v_mov_b32_e32 v55, v32
	s_branch .LBB0_88
.LBB0_87:
	s_or_b64 exec, exec, s[4:5]
	s_nop 4
	v_cvt_f32_i32_e32 v73, v87
	v_mul_f32_e32 v72, 0x3e000000, v72
	v_cmp_ge_i32_e32 vcc, v82, v88
	v_or_b32_e32 v92, 3, v88
	v_mul_f32_e32 v73, v90, v73
	v_mul_f32_e32 v73, 0x3fb8aa3b, v73
	v_exp_f32_e32 v73, v73
	v_or_b32_e32 v93, 2, v88
	s_mov_b32 s4, 0x3e000000
	v_pk_mul_f32 v[74:75], v[74:75], s[4:5] op_sel_hi:[1,0]
	v_mul_f32_e32 v72, v72, v73
	v_cndmask_b32_e32 v91, 0, v72, vcc
	v_sub_u32_e32 v72, v82, v93
	v_sub_u32_e32 v73, v82, v92
	v_cvt_f32_i32_e32 v72, v72
	v_cvt_f32_i32_e32 v73, v73
	v_cmp_ge_i32_e32 vcc, v82, v93
	s_mov_b32 s4, 0x5040100
	v_mul_f32_e32 v72, v90, v72
	v_mul_f32_e32 v73, v90, v73
	v_mul_f32_e32 v72, 0x3fb8aa3b, v72
	v_mul_f32_e32 v73, 0x3fb8aa3b, v73
	v_exp_f32_e32 v72, v72
	v_exp_f32_e32 v73, v73
	v_add_u32_e32 v84, -1, v84
	v_add_u32_e32 v86, 0x900, v86
	v_add_u32_e32 v88, 16, v88
	v_pk_mul_f32 v[72:73], v[74:75], v[72:73]
	v_cvt_pk_bf16_f32 v74, v91, v89
	v_cvt_pk_bf16_f32 v72, v72, v73
	v_cndmask_b32_e32 v73, 0, v72, vcc
	v_lshrrev_b32_e32 v72, 16, v72
	v_cmp_ge_i32_e32 vcc, v77, v92
	v_add_u32_e32 v89, 0, v85
	v_add_u32_e32 v85, 32, v85
	v_cndmask_b32_e32 v72, 0, v72, vcc
	v_perm_b32 v75, v72, v73, s4
	ds_read_b64 v[128:129], v89 offset:36864
	ds_read_b64 v[130:131], v89 offset:41216
	ds_read_b64 v[132:133], v89 offset:45568
	ds_read_b64 v[134:135], v89 offset:49920
	ds_read_b64 v[136:137], v89 offset:54272
	ds_read_b64 v[138:139], v89 offset:58624
	ds_read_b64 v[140:141], v89 offset:62976
	v_add_u32_e32 v72, 0x10700, v89
	ds_read_b64 v[142:143], v72
	v_cmp_eq_u32_e32 vcc, 0, v84
	v_add_u32_e32 v87, -16, v87
	s_nop 0
	s_or_b64 s[2:3], vcc, s[2:3]
	s_waitcnt lgkmcnt(7)
	v_mfma_f32_16x16x16_bf16 v[32:35], v[74:75], v[128:129], v[32:35]
	s_waitcnt lgkmcnt(6)
	v_mfma_f32_16x16x16_bf16 v[36:39], v[74:75], v[130:131], v[36:39]
	s_waitcnt lgkmcnt(5)
	v_mfma_f32_16x16x16_bf16 v[56:59], v[74:75], v[132:133], v[56:59]
	s_waitcnt lgkmcnt(4)
	v_mfma_f32_16x16x16_bf16 v[60:63], v[74:75], v[134:135], v[60:63]
	s_waitcnt lgkmcnt(3)
	v_mfma_f32_16x16x16_bf16 v[40:43], v[74:75], v[136:137], v[40:43]
	s_waitcnt lgkmcnt(2)
	v_mfma_f32_16x16x16_bf16 v[48:51], v[74:75], v[138:139], v[48:51]
	s_waitcnt lgkmcnt(1)
	v_mfma_f32_16x16x16_bf16 v[44:47], v[74:75], v[140:141], v[44:47]
	s_waitcnt lgkmcnt(0)
	v_mfma_f32_16x16x16_bf16 v[52:55], v[74:75], v[142:143], v[52:55]
	s_andn2_b64 exec, exec, s[2:3]
	s_cbranch_execz .LBB0_90

; DEV f32x4 mfma32(bf16x8 a, bf16x8 b, f32x4 c) { return __builtin_amdgcn_mfma_f32_16x16x32_bf16(a, b, c, 0, 0, 0); }
; template <int R>
; DEV void sg_core(const bf16_t* __restrict__ A, int lda, const bf16_t* __restrict__ Bt, int ldb, int K, int row0, int col0, f32x4 (&acc)[2], unsigned char* smem) {
;     ...
; #pragma unroll
;       for (int ks = 0; ks < 2; ++ks) {
;         const bf16x8 af = *(const bf16x8*)(cur + aoff + ks * 64);
; #pragma unroll
;         for (int ni = 0; ni < 2; ++ni) {
;           const bf16x8 bfr = *(const bf16x8*)(cur + boff + ni * 16 * 144 + ks * 64);
;           acc[ni] = mfma32(bfr, af, acc[ni]);
;         }
;       }
;       asm volatile("s_waitcnt lgkmcnt(0)\n\ts_barrier" ::: "memory");
;     }
.LBB0_99:
	ds_read_b128 v[184:187], v177 offset:18432
	ds_read_b128 v[188:191], v179 offset:27648
	ds_read_b128 v[192:195], v179 offset:29952
	ds_read_b128 v[196:199], v177 offset:18496
	ds_read_b128 v[220:223], v179 offset:27712
	ds_read_b128 v[224:227], v179 offset:30016
	s_mov_b64 s[14:15], 0
	s_andn2_b64 vcc, exec, s[12:13]
	s_waitcnt lgkmcnt(4)
	v_mfma_f32_16x16x32_bf16 v[160:163], v[188:191], v[184:187], v[160:163]
	s_waitcnt lgkmcnt(3)
	v_mfma_f32_16x16x32_bf16 v[184:187], v[192:195], v[184:187], v[164:167]
	s_waitcnt lgkmcnt(1)
	v_mfma_f32_16x16x32_bf16 v[164:167], v[220:223], v[196:199], v[160:163]
	s_waitcnt lgkmcnt(0)
	v_mfma_f32_16x16x32_bf16 v[160:163], v[224:227], v[196:199], v[184:187]
	s_waitcnt lgkmcnt(0)
	s_barrier
	s_cbranch_vccz .LBB0_97

; DEV f32x4 mfma32(bf16x8 a, bf16x8 b, f32x4 c) { return __builtin_amdgcn_mfma_f32_16x16x32_bf16(a, b, c, 0, 0, 0); }
; template <int R>
; DEV void sg_core(const bf16_t* __restrict__ A, int lda, const bf16_t* __restrict__ Bt, int ldb, int K, int row0, int col0, f32x4 (&acc)[2], unsigned char* smem) {
;     ...
;   for (int kt0 = 0; kt0 < nt; kt0 += R) {
; #pragma unroll
;     for (int u = 0; u < R; ++u) {
;       const int kt = kt0 + u;
;       unsigned char* cur = smem + (u & 1) * 18432;
;       unsigned char* nxt = smem + ((u + 1) & 1) * 18432;
;       if (kt + 1 < nt) { *(u32x4*)(nxt + woff) = ra[(u + 1) % R]; *(u32x4*)(nxt + 9216 + woff) = rb[(u + 1) % R]; }
;       if (kt + R < nt) { ra[u] = *(const u32x4*)(pa + (size_t)(kt + R) * 64); rb[u] = *(const u32x4*)(pb + (size_t)(kt + R) * 64); }
; #pragma unroll
;       for (int ks = 0; ks < 2; ++ks) {
;         const bf16x8 af = *(const bf16x8*)(cur + aoff + ks * 64);
; #pragma unroll
;         for (int ni = 0; ni < 2; ++ni) {
;           const bf16x8 bfr = *(const bf16x8*)(cur + boff + ni * 16 * 144 + ks * 64);
;           acc[ni] = mfma32(bfr, af, acc[ni]);
;         }
;       }
;       asm volatile("s_waitcnt lgkmcnt(0)\n\ts_barrier" ::: "memory");
;     }
.LBB0_102:
	ds_read_b128 v[184:187], v177
	ds_read_b128 v[188:191], v179 offset:9216
	ds_read_b128 v[192:195], v179 offset:11520
	ds_read_b128 v[196:199], v177 offset:64
	ds_read_b128 v[220:223], v179 offset:9280
	ds_read_b128 v[224:227], v179 offset:11584
	s_andn2_b64 vcc, exec, s[14:15]
	s_waitcnt lgkmcnt(4)
	v_mfma_f32_16x16x32_bf16 v[164:167], v[188:191], v[184:187], v[164:167]
	s_waitcnt lgkmcnt(3)
	v_mfma_f32_16x16x32_bf16 v[184:187], v[192:195], v[184:187], v[160:163]
	s_waitcnt lgkmcnt(1)
	v_mfma_f32_16x16x32_bf16 v[160:163], v[220:223], v[196:199], v[164:167]
	s_waitcnt lgkmcnt(0)
	v_mfma_f32_16x16x32_bf16 v[164:167], v[224:227], v[196:199], v[184:187]
	s_waitcnt lgkmcnt(0)
	s_barrier
	s_waitcnt vmcnt(11)
	ds_write_b128 v168, v[108:111]
	s_waitcnt vmcnt(10)
	ds_write_b128 v168, v[112:115] offset:9216
	s_nop 2
	v_cndmask_b32_e64 v184, 0, 1, s[14:15]
	v_cmp_ne_u32_e64 s[38:39], 1, v184
	s_cbranch_vccnz .LBB0_104
	global_load_dwordx4 v[100:103], v[180:181], off offset:1152
	global_load_dwordx4 v[104:107], v[182:183], off offset:1152
.LBB0_104:
	ds_read_b128 v[184:187], v177 offset:18432
	ds_read_b128 v[188:191], v179 offset:27648
	ds_read_b128 v[192:195], v179 offset:29952
	ds_read_b128 v[196:199], v177 offset:18496
	ds_read_b128 v[220:223], v179 offset:27712
	ds_read_b128 v[224:227], v179 offset:30016
	s_and_b64 vcc, exec, s[38:39]
	s_waitcnt lgkmcnt(4)
	v_mfma_f32_16x16x32_bf16 v[160:163], v[188:191], v[184:187], v[160:163]
	s_waitcnt lgkmcnt(3)
	v_mfma_f32_16x16x32_bf16 v[164:167], v[192:195], v[184:187], v[164:167]
	s_waitcnt lgkmcnt(1)
	v_mfma_f32_16x16x32_bf16 v[160:163], v[220:223], v[196:199], v[160:163]
	s_waitcnt lgkmcnt(0)
	v_mfma_f32_16x16x32_bf16 v[164:167], v[224:227], v[196:199], v[164:167]
	s_waitcnt lgkmcnt(0)
	s_barrier
	s_waitcnt vmcnt(9)
	ds_write_b128 v168, v[120:123] offset:18432
	s_waitcnt vmcnt(8)
	ds_write_b128 v168, v[124:127] offset:27648
	s_cbranch_vccnz .LBB0_106
	global_load_dwordx4 v[108:111], v[180:181], off offset:1280
	global_load_dwordx4 v[112:115], v[182:183], off offset:1280
.LBB0_106:
	ds_read_b128 v[184:187], v177
	ds_read_b128 v[188:191], v179 offset:9216
	ds_read_b128 v[192:195], v179 offset:11520
	ds_read_b128 v[196:199], v177 offset:64
	ds_read_b128 v[220:223], v179 offset:9280
	ds_read_b128 v[224:227], v179 offset:11584
	s_and_b64 vcc, exec, s[38:39]
	s_waitcnt lgkmcnt(4)
	v_mfma_f32_16x16x32_bf16 v[160:163], v[188:191], v[184:187], v[160:163]
	s_waitcnt lgkmcnt(3)
	v_mfma_f32_16x16x32_bf16 v[164:167], v[192:195], v[184:187], v[164:167]
	s_waitcnt lgkmcnt(1)
	v_mfma_f32_16x16x32_bf16 v[160:163], v[220:223], v[196:199], v[160:163]
	s_waitcnt lgkmcnt(0)
	v_mfma_f32_16x16x32_bf16 v[164:167], v[224:227], v[196:199], v[164:167]
	s_waitcnt lgkmcnt(0)
	s_barrier
	s_waitcnt vmcnt(7)
	ds_write_b128 v168, v[128:131]
	s_waitcnt vmcnt(6)
	ds_write_b128 v168, v[132:135] offset:9216
	s_cbranch_vccnz .LBB0_108
	global_load_dwordx4 v[120:123], v[180:181], off offset:1408
	global_load_dwordx4 v[124:127], v[182:183], off offset:1408
.LBB0_108:
	ds_read_b128 v[184:187], v177 offset:18432
	ds_read_b128 v[188:191], v179 offset:27648
	ds_read_b128 v[192:195], v179 offset:29952
	ds_read_b128 v[196:199], v177 offset:18496
	ds_read_b128 v[220:223], v179 offset:27712
	ds_read_b128 v[224:227], v179 offset:30016
	s_and_b64 vcc, exec, s[38:39]
	s_waitcnt lgkmcnt(4)
	v_mfma_f32_16x16x32_bf16 v[160:163], v[188:191], v[184:187], v[160:163]
	s_waitcnt lgkmcnt(3)
	v_mfma_f32_16x16x32_bf16 v[164:167], v[192:195], v[184:187], v[164:167]
	s_waitcnt lgkmcnt(1)
	v_mfma_f32_16x16x32_bf16 v[160:163], v[220:223], v[196:199], v[160:163]
	s_waitcnt lgkmcnt(0)
	v_mfma_f32_16x16x32_bf16 v[164:167], v[224:227], v[196:199], v[164:167]
	s_waitcnt lgkmcnt(0)
	s_barrier
	s_waitcnt vmcnt(5)
	ds_write_b128 v168, v[136:139] offset:18432
	s_waitcnt vmcnt(4)
	ds_write_b128 v168, v[140:143] offset:27648
	s_cbranch_vccnz .LBB0_110
	global_load_dwordx4 v[128:131], v[180:181], off offset:1536
	global_load_dwordx4 v[132:135], v[182:183], off offset:1536
.LBB0_110:
	ds_read_b128 v[184:187], v177
	ds_read_b128 v[188:191], v179 offset:9216
	ds_read_b128 v[192:195], v179 offset:11520
	ds_read_b128 v[196:199], v177 offset:64
	ds_read_b128 v[220:223], v179 offset:9280
	ds_read_b128 v[224:227], v179 offset:11584
	s_and_b64 vcc, exec, s[38:39]
	s_waitcnt lgkmcnt(4)
	v_mfma_f32_16x16x32_bf16 v[160:163], v[188:191], v[184:187], v[160:163]
	s_waitcnt lgkmcnt(3)
	v_mfma_f32_16x16x32_bf16 v[164:167], v[192:195], v[184:187], v[164:167]
	s_waitcnt lgkmcnt(1)
	v_mfma_f32_16x16x32_bf16 v[160:163], v[220:223], v[196:199], v[160:163]
	s_waitcnt lgkmcnt(0)
	v_mfma_f32_16x16x32_bf16 v[164:167], v[224:227], v[196:199], v[164:167]
	s_waitcnt lgkmcnt(0)
	s_barrier
	s_waitcnt vmcnt(1)
	ds_write_b128 v168, v[144:147]
	s_waitcnt vmcnt(0)
	ds_write_b128 v168, v[148:151] offset:9216
	s_cbranch_vccnz .LBB0_112
	global_load_dwordx4 v[136:139], v[180:181], off offset:1664
	global_load_dwordx4 v[140:143], v[182:183], off offset:1664
.LBB0_112:
	ds_read_b128 v[184:187], v177 offset:18432
	ds_read_b128 v[188:191], v179 offset:27648
	ds_read_b128 v[192:195], v179 offset:29952
	ds_read_b128 v[196:199], v177 offset:18496
	ds_read_b128 v[220:223], v179 offset:27712
	ds_read_b128 v[224:227], v179 offset:30016
	s_and_b64 vcc, exec, s[38:39]
	s_waitcnt lgkmcnt(4)
	v_mfma_f32_16x16x32_bf16 v[160:163], v[188:191], v[184:187], v[160:163]
	s_waitcnt lgkmcnt(3)
	v_mfma_f32_16x16x32_bf16 v[164:167], v[192:195], v[184:187], v[164:167]
	s_waitcnt lgkmcnt(1)
	v_mfma_f32_16x16x32_bf16 v[160:163], v[220:223], v[196:199], v[160:163]
	s_waitcnt lgkmcnt(0)
	v_mfma_f32_16x16x32_bf16 v[164:167], v[224:227], v[196:199], v[164:167]
	s_waitcnt lgkmcnt(0)
	s_barrier
	s_waitcnt vmcnt(1)
	ds_write_b128 v168, v[152:155] offset:18432
	s_waitcnt vmcnt(0)
	ds_write_b128 v168, v[156:159] offset:27648
	s_cbranch_vccnz .LBB0_114
	global_load_dwordx4 v[144:147], v[180:181], off offset:1792
	global_load_dwordx4 v[148:151], v[182:183], off offset:1792

; template <class Epi, bool SEQ>
; DEV void gemm_phase(PG8_LAS unsigned char* lds, const Gemm g, const Epi& E) {
;     ...
;     if (!keep) {
; #pragma unroll
;       for (int a = 0; a < 2; ++a)
; #pragma unroll
;         for (int b = 0; b < 2; ++b)
; #pragma unroll
;           for (int m = 0; m < 4; ++m)
; #pragma unroll
;             for (int n = 0; n < 2; ++n) acc[a][b][m][n] = (f32x4){0.f, 0.f, 0.f, 0.f};
.LBB0_170:
	s_add_u32 s26, s26, 0x80
	s_addc_u32 s27, s27, 0
	s_add_u32 s5, s36, 0x100
	v_mov_b64_e32 v[0:1], 0
	v_mov_b64_e32 v[2:3], 0
	v_mov_b64_e32 v[4:5], 0
	v_mov_b64_e32 v[6:7], 0
	v_mov_b64_e32 v[8:9], 0
	v_mov_b64_e32 v[10:11], 0
	v_mov_b64_e32 v[12:13], 0
	v_mov_b64_e32 v[14:15], 0
	v_mov_b64_e32 v[16:17], 0
	v_mov_b64_e32 v[18:19], 0
	v_mov_b64_e32 v[20:21], 0
	v_mov_b64_e32 v[22:23], 0
	v_mov_b64_e32 v[24:25], 0
	v_mov_b64_e32 v[26:27], 0
	v_mov_b64_e32 v[28:29], 0
	v_mov_b64_e32 v[30:31], 0
	v_mov_b64_e32 v[32:33], 0
	v_mov_b64_e32 v[34:35], 0
	v_mov_b64_e32 v[36:37], 0
	v_mov_b64_e32 v[38:39], 0
	v_mov_b64_e32 v[40:41], 0
	v_mov_b64_e32 v[42:43], 0
	v_mov_b64_e32 v[44:45], 0
	v_mov_b64_e32 v[46:47], 0
	v_mov_b64_e32 v[48:49], 0
	v_mov_b64_e32 v[50:51], 0
	v_mov_b64_e32 v[52:53], 0
	v_mov_b64_e32 v[54:55], 0
	v_mov_b64_e32 v[56:57], 0
	v_mov_b64_e32 v[58:59], 0
	v_mov_b64_e32 v[60:61], 0
	v_mov_b64_e32 v[62:63], 0
	v_mov_b64_e32 v[64:65], 0
	v_mov_b64_e32 v[66:67], 0
	v_mov_b64_e32 v[68:69], 0
	v_mov_b64_e32 v[70:71], 0
	v_mov_b64_e32 v[72:73], 0
	v_mov_b64_e32 v[74:75], 0
	v_mov_b64_e32 v[76:77], 0
	v_mov_b64_e32 v[78:79], 0
	v_mov_b64_e32 v[80:81], 0
	v_mov_b64_e32 v[82:83], 0
	v_mov_b64_e32 v[84:85], 0
	v_mov_b64_e32 v[86:87], 0
	v_mov_b64_e32 v[88:89], 0
	v_mov_b64_e32 v[90:91], 0
	v_mov_b64_e32 v[92:93], 0
	v_mov_b64_e32 v[94:95], 0
	v_mov_b64_e32 v[96:97], 0
	v_mov_b64_e32 v[98:99], 0
	v_mov_b64_e32 v[100:101], 0
	v_mov_b64_e32 v[102:103], 0
	v_mov_b64_e32 v[104:105], 0
	v_mov_b64_e32 v[106:107], 0
	v_mov_b64_e32 v[108:109], 0
	v_mov_b64_e32 v[110:111], 0
	v_mov_b64_e32 v[112:113], 0
	v_mov_b64_e32 v[114:115], 0
	v_mov_b64_e32 v[116:117], 0
	v_mov_b64_e32 v[118:119], 0
	v_mov_b64_e32 v[120:121], 0
	v_mov_b64_e32 v[122:123], 0
	v_mov_b64_e32 v[124:125], 0
	v_mov_b64_e32 v[126:127], 0
	s_addc_u32 s15, s37, 0
	s_mov_b32 s17, 0

; template <class Epi, bool SEQ>
; DEV void gemm_phase(PG8_LAS unsigned char* lds, const Gemm g, const Epi& E) {
;     ...
;     const bool has_next = next_unit<SEQ>(g, ui + 1, G, cblk, nxt);
;     const char* nA = has_next ? PG8_ABASE(nxt) : cA; const char* nB = has_next ? PG8_BBASE(nxt) : cB;
;     ...
;     if (!keep) {
; #pragma unroll
;       for (int a = 0; a < 2; ++a)
; #pragma unroll
;         for (int b = 0; b < 2; ++b)
; #pragma unroll
;           for (int m = 0; m < 4; ++m)
; #pragma unroll
;             for (int n = 0; n < 2; ++n) acc[a][b][m][n] = (f32x4){0.f, 0.f, 0.f, 0.f};
.LBB0_204:
	s_ashr_i32 s5, s4, 31
	s_lshl_b64 s[14:15], s[4:5], 19
	s_add_u32 s14, s24, s14
	s_addc_u32 s15, s25, s15
	s_and_b64 s[16:17], s[12:13], exec
	s_cselect_b32 s5, s15, s19
	s_cselect_b32 s48, s14, s18
	s_ashr_i32 s9, s8, 31
	s_lshl_b64 s[16:17], s[8:9], 19
	s_add_u32 s16, s37, s16
	s_addc_u32 s17, s38, s17
	s_and_b64 s[26:27], s[12:13], exec
	s_cselect_b32 s9, s17, s21
	s_cselect_b32 s49, s16, s20
	s_add_u32 s18, s18, 0x40080
	s_addc_u32 s19, s19, 0
	s_add_u32 s50, s20, 0x100
	v_mov_b64_e32 v[0:1], 0
	v_mov_b64_e32 v[2:3], 0
	v_mov_b64_e32 v[4:5], 0
	v_mov_b64_e32 v[6:7], 0
	v_mov_b64_e32 v[8:9], 0
	v_mov_b64_e32 v[10:11], 0
	v_mov_b64_e32 v[12:13], 0
	v_mov_b64_e32 v[14:15], 0
	v_mov_b64_e32 v[16:17], 0
	v_mov_b64_e32 v[18:19], 0
	v_mov_b64_e32 v[20:21], 0
	v_mov_b64_e32 v[22:23], 0
	v_mov_b64_e32 v[24:25], 0
	v_mov_b64_e32 v[26:27], 0
	v_mov_b64_e32 v[28:29], 0
	v_mov_b64_e32 v[30:31], 0
	v_mov_b64_e32 v[32:33], 0
	v_mov_b64_e32 v[34:35], 0
	v_mov_b64_e32 v[36:37], 0
	v_mov_b64_e32 v[38:39], 0
	v_mov_b64_e32 v[40:41], 0
	v_mov_b64_e32 v[42:43], 0
	v_mov_b64_e32 v[44:45], 0
	v_mov_b64_e32 v[46:47], 0
	v_mov_b64_e32 v[48:49], 0
	v_mov_b64_e32 v[50:51], 0
	v_mov_b64_e32 v[52:53], 0
	v_mov_b64_e32 v[54:55], 0
	v_mov_b64_e32 v[56:57], 0
	v_mov_b64_e32 v[58:59], 0
	v_mov_b64_e32 v[60:61], 0
	v_mov_b64_e32 v[62:63], 0
	v_mov_b64_e32 v[64:65], 0
	v_mov_b64_e32 v[66:67], 0
	v_mov_b64_e32 v[68:69], 0
	v_mov_b64_e32 v[70:71], 0
	v_mov_b64_e32 v[72:73], 0
	v_mov_b64_e32 v[74:75], 0
	v_mov_b64_e32 v[76:77], 0
	v_mov_b64_e32 v[78:79], 0
	v_mov_b64_e32 v[80:81], 0
	v_mov_b64_e32 v[82:83], 0
	v_mov_b64_e32 v[84:85], 0
	v_mov_b64_e32 v[86:87], 0
	v_mov_b64_e32 v[88:89], 0
	v_mov_b64_e32 v[90:91], 0
	v_mov_b64_e32 v[92:93], 0
	v_mov_b64_e32 v[94:95], 0
	v_mov_b64_e32 v[96:97], 0
	v_mov_b64_e32 v[98:99], 0
	v_mov_b64_e32 v[100:101], 0
	v_mov_b64_e32 v[102:103], 0
	v_mov_b64_e32 v[104:105], 0
	v_mov_b64_e32 v[106:107], 0
	v_mov_b64_e32 v[108:109], 0
	v_mov_b64_e32 v[110:111], 0
	v_mov_b64_e32 v[112:113], 0
	v_mov_b64_e32 v[114:115], 0
	v_mov_b64_e32 v[116:117], 0
	v_mov_b64_e32 v[118:119], 0
	v_mov_b64_e32 v[120:121], 0
	v_mov_b64_e32 v[122:123], 0
	v_mov_b64_e32 v[124:125], 0
	v_mov_b64_e32 v[126:127], 0
	s_addc_u32 s51, s21, 0
	s_mov_b32 s52, -2
	s_waitcnt lgkmcnt(0)

; template <class Epi, bool SEQ>
; DEV void gemm_phase(PG8_LAS unsigned char* lds, const Gemm g, const Epi& E) {
;     ...
;     const bool has_next = next_unit<SEQ>(g, ui + 1, G, cblk, nxt);
;     const char* nA = has_next ? PG8_ABASE(nxt) : cA; const char* nB = has_next ? PG8_BBASE(nxt) : cB;
;     ...
;     if (!keep) {
; #pragma unroll
;       for (int a = 0; a < 2; ++a)
; #pragma unroll
;         for (int b = 0; b < 2; ++b)
; #pragma unroll
;           for (int m = 0; m < 4; ++m)
; #pragma unroll
;             for (int n = 0; n < 2; ++n) acc[a][b][m][n] = (f32x4){0.f, 0.f, 0.f, 0.f};
.LBB0_286:
	s_ashr_i32 s13, s12, 31
	s_lshl_b64 s[16:17], s[12:13], 19
	s_add_u32 s16, s24, s16
	s_addc_u32 s17, s25, s17
	s_and_b64 s[18:19], s[8:9], exec
	s_cselect_b32 s13, s17, s21
	s_cselect_b32 s49, s16, s20
	s_ashr_i32 s15, s14, 31
	s_lshl_b64 s[18:19], s[14:15], 19
	s_add_u32 s18, s0, s18
	s_addc_u32 s19, s1, s19
	s_and_b64 s[36:37], s[8:9], exec
	s_cselect_b32 s15, s19, s27
	s_cselect_b32 s50, s18, s26
	s_add_u32 s20, s20, 0x40080
	s_addc_u32 s21, s21, 0
	s_add_u32 s51, s26, 0x100
	v_mov_b64_e32 v[0:1], 0
	v_mov_b64_e32 v[2:3], 0
	v_mov_b64_e32 v[4:5], 0
	v_mov_b64_e32 v[6:7], 0
	v_mov_b64_e32 v[8:9], 0
	v_mov_b64_e32 v[10:11], 0
	v_mov_b64_e32 v[12:13], 0
	v_mov_b64_e32 v[14:15], 0
	v_mov_b64_e32 v[16:17], 0
	v_mov_b64_e32 v[18:19], 0
	v_mov_b64_e32 v[20:21], 0
	v_mov_b64_e32 v[22:23], 0
	v_mov_b64_e32 v[24:25], 0
	v_mov_b64_e32 v[26:27], 0
	v_mov_b64_e32 v[28:29], 0
	v_mov_b64_e32 v[30:31], 0
	v_mov_b64_e32 v[32:33], 0
	v_mov_b64_e32 v[34:35], 0
	v_mov_b64_e32 v[36:37], 0
	v_mov_b64_e32 v[38:39], 0
	v_mov_b64_e32 v[40:41], 0
	v_mov_b64_e32 v[42:43], 0
	v_mov_b64_e32 v[44:45], 0
	v_mov_b64_e32 v[46:47], 0
	v_mov_b64_e32 v[48:49], 0
	v_mov_b64_e32 v[50:51], 0
	v_mov_b64_e32 v[52:53], 0
	v_mov_b64_e32 v[54:55], 0
	v_mov_b64_e32 v[56:57], 0
	v_mov_b64_e32 v[58:59], 0
	v_mov_b64_e32 v[60:61], 0
	v_mov_b64_e32 v[62:63], 0
	v_mov_b64_e32 v[64:65], 0
	v_mov_b64_e32 v[66:67], 0
	v_mov_b64_e32 v[68:69], 0
	v_mov_b64_e32 v[70:71], 0
	v_mov_b64_e32 v[72:73], 0
	v_mov_b64_e32 v[74:75], 0
	v_mov_b64_e32 v[76:77], 0
	v_mov_b64_e32 v[78:79], 0
	v_mov_b64_e32 v[80:81], 0
	v_mov_b64_e32 v[82:83], 0
	v_mov_b64_e32 v[84:85], 0
	v_mov_b64_e32 v[86:87], 0
	v_mov_b64_e32 v[88:89], 0
	v_mov_b64_e32 v[90:91], 0
	v_mov_b64_e32 v[92:93], 0
	v_mov_b64_e32 v[94:95], 0
	v_mov_b64_e32 v[96:97], 0
	v_mov_b64_e32 v[98:99], 0
	v_mov_b64_e32 v[100:101], 0
	v_mov_b64_e32 v[102:103], 0
	v_mov_b64_e32 v[104:105], 0
	v_mov_b64_e32 v[106:107], 0
	v_mov_b64_e32 v[108:109], 0
	v_mov_b64_e32 v[110:111], 0
	v_mov_b64_e32 v[112:113], 0
	v_mov_b64_e32 v[114:115], 0
	v_mov_b64_e32 v[116:117], 0
	v_mov_b64_e32 v[118:119], 0
	v_mov_b64_e32 v[120:121], 0
	v_mov_b64_e32 v[122:123], 0
	v_mov_b64_e32 v[124:125], 0
	v_mov_b64_e32 v[126:127], 0
	s_addc_u32 s52, s27, 0
	s_mov_b32 s53, -2

; template <class Epi, bool SEQ>
; DEV void gemm_phase(PG8_LAS unsigned char* lds, const Gemm g, const Epi& E) {
;     ...
;     if (!keep) {
; #pragma unroll
;       for (int a = 0; a < 2; ++a)
; #pragma unroll
;         for (int b = 0; b < 2; ++b)
; #pragma unroll
;           for (int m = 0; m < 4; ++m)
; #pragma unroll
;             for (int n = 0; n < 2; ++n) acc[a][b][m][n] = (f32x4){0.f, 0.f, 0.f, 0.f};
;     }
.LBB0_322:
	s_and_b64 vcc, exec, s[38:39]
	s_mov_b64 s[18:19], -1
	s_cbranch_vccnz .LBB0_307
	s_andn2_b64 vcc, exec, s[0:1]
	s_cbranch_vccnz .LBB0_325
	v_mov_b64_e32 v[0:1], 0
	v_mov_b64_e32 v[2:3], 0
	v_mov_b64_e32 v[4:5], 0
	v_mov_b64_e32 v[6:7], 0
	v_mov_b64_e32 v[8:9], 0
	v_mov_b64_e32 v[10:11], 0
	v_mov_b64_e32 v[12:13], 0
	v_mov_b64_e32 v[14:15], 0
	v_mov_b64_e32 v[16:17], 0
	v_mov_b64_e32 v[18:19], 0
	v_mov_b64_e32 v[20:21], 0
	v_mov_b64_e32 v[22:23], 0
	v_mov_b64_e32 v[24:25], 0
	v_mov_b64_e32 v[26:27], 0
	v_mov_b64_e32 v[28:29], 0
	v_mov_b64_e32 v[30:31], 0
	v_mov_b64_e32 v[32:33], 0
	v_mov_b64_e32 v[34:35], 0
	v_mov_b64_e32 v[36:37], 0
	v_mov_b64_e32 v[38:39], 0
	v_mov_b64_e32 v[40:41], 0
	v_mov_b64_e32 v[42:43], 0
	v_mov_b64_e32 v[44:45], 0
	v_mov_b64_e32 v[46:47], 0
	v_mov_b64_e32 v[48:49], 0
	v_mov_b64_e32 v[50:51], 0
	v_mov_b64_e32 v[52:53], 0
	v_mov_b64_e32 v[54:55], 0
	v_mov_b64_e32 v[56:57], 0
	v_mov_b64_e32 v[58:59], 0
	v_mov_b64_e32 v[60:61], 0
	v_mov_b64_e32 v[62:63], 0
	v_mov_b64_e32 v[64:65], 0
	v_mov_b64_e32 v[66:67], 0
	v_mov_b64_e32 v[68:69], 0
	v_mov_b64_e32 v[70:71], 0
	v_mov_b64_e32 v[72:73], 0
	v_mov_b64_e32 v[74:75], 0
	v_mov_b64_e32 v[76:77], 0
	v_mov_b64_e32 v[78:79], 0
	v_mov_b64_e32 v[80:81], 0
	v_mov_b64_e32 v[82:83], 0
	v_mov_b64_e32 v[84:85], 0
	v_mov_b64_e32 v[86:87], 0
	v_mov_b64_e32 v[88:89], 0
	v_mov_b64_e32 v[90:91], 0
	v_mov_b64_e32 v[92:93], 0
	v_mov_b64_e32 v[94:95], 0
	v_mov_b64_e32 v[96:97], 0
	v_mov_b64_e32 v[98:99], 0
	v_mov_b64_e32 v[100:101], 0
	v_mov_b64_e32 v[102:103], 0
	v_mov_b64_e32 v[104:105], 0
	v_mov_b64_e32 v[106:107], 0
	v_mov_b64_e32 v[108:109], 0
	v_mov_b64_e32 v[110:111], 0
	v_mov_b64_e32 v[112:113], 0
	v_mov_b64_e32 v[114:115], 0
	v_mov_b64_e32 v[116:117], 0
	v_mov_b64_e32 v[118:119], 0
	v_mov_b64_e32 v[120:121], 0
	v_mov_b64_e32 v[122:123], 0
	v_mov_b64_e32 v[124:125], 0
	v_mov_b64_e32 v[126:127], 0

; template <class Epi, bool SEQ>
; DEV void gemm_phase(PG8_LAS unsigned char* lds, const Gemm g, const Epi& E) {
;     ...
;     const bool has_next = next_unit<SEQ>(g, ui + 1, G, cblk, nxt);
;     const char* nA = has_next ? PG8_ABASE(nxt) : cA; const char* nB = has_next ? PG8_BBASE(nxt) : cB;
;     ...
;     if (!keep) {
; #pragma unroll
;       for (int a = 0; a < 2; ++a)
; #pragma unroll
;         for (int b = 0; b < 2; ++b)
; #pragma unroll
;           for (int m = 0; m < 4; ++m)
; #pragma unroll
;             for (int n = 0; n < 2; ++n) acc[a][b][m][n] = (f32x4){0.f, 0.f, 0.f, 0.f};
.LBB0_498:
	s_ashr_i32 s13, s12, 31
	s_lshl_b64 s[14:15], s[12:13], 19
	s_add_u32 s14, s24, s14
	s_addc_u32 s15, s25, s15
	s_and_b64 s[16:17], s[4:5], exec
	s_cselect_b32 s13, s15, s19
	s_cselect_b32 s44, s14, s18
	s_ashr_i32 s9, s8, 31
	s_lshl_b64 s[16:17], s[8:9], 19
	s_add_u32 s16, s28, s16
	s_addc_u32 s17, s29, s17
	s_and_b64 s[26:27], s[4:5], exec
	s_cselect_b32 s9, s17, s21
	s_cselect_b32 s45, s16, s20
	s_add_u32 s18, s18, 0x40080
	s_addc_u32 s19, s19, 0
	s_add_u32 s46, s20, 0x100
	v_mov_b64_e32 v[0:1], 0
	v_mov_b64_e32 v[2:3], 0
	v_mov_b64_e32 v[4:5], 0
	v_mov_b64_e32 v[6:7], 0
	v_mov_b64_e32 v[8:9], 0
	v_mov_b64_e32 v[10:11], 0
	v_mov_b64_e32 v[12:13], 0
	v_mov_b64_e32 v[14:15], 0
	v_mov_b64_e32 v[16:17], 0
	v_mov_b64_e32 v[18:19], 0
	v_mov_b64_e32 v[20:21], 0
	v_mov_b64_e32 v[22:23], 0
	v_mov_b64_e32 v[24:25], 0
	v_mov_b64_e32 v[26:27], 0
	v_mov_b64_e32 v[28:29], 0
	v_mov_b64_e32 v[30:31], 0
	v_mov_b64_e32 v[32:33], 0
	v_mov_b64_e32 v[34:35], 0
	v_mov_b64_e32 v[36:37], 0
	v_mov_b64_e32 v[38:39], 0
	v_mov_b64_e32 v[40:41], 0
	v_mov_b64_e32 v[42:43], 0
	v_mov_b64_e32 v[44:45], 0
	v_mov_b64_e32 v[46:47], 0
	v_mov_b64_e32 v[48:49], 0
	v_mov_b64_e32 v[50:51], 0
	v_mov_b64_e32 v[52:53], 0
	v_mov_b64_e32 v[54:55], 0
	v_mov_b64_e32 v[56:57], 0
	v_mov_b64_e32 v[58:59], 0
	v_mov_b64_e32 v[60:61], 0
	v_mov_b64_e32 v[62:63], 0
	v_mov_b64_e32 v[64:65], 0
	v_mov_b64_e32 v[66:67], 0
	v_mov_b64_e32 v[68:69], 0
	v_mov_b64_e32 v[70:71], 0
	v_mov_b64_e32 v[72:73], 0
	v_mov_b64_e32 v[74:75], 0
	v_mov_b64_e32 v[76:77], 0
	v_mov_b64_e32 v[78:79], 0
	v_mov_b64_e32 v[80:81], 0
	v_mov_b64_e32 v[82:83], 0
	v_mov_b64_e32 v[84:85], 0
	v_mov_b64_e32 v[86:87], 0
	v_mov_b64_e32 v[88:89], 0
	v_mov_b64_e32 v[90:91], 0
	v_mov_b64_e32 v[92:93], 0
	v_mov_b64_e32 v[94:95], 0
	v_mov_b64_e32 v[96:97], 0
	v_mov_b64_e32 v[98:99], 0
	v_mov_b64_e32 v[100:101], 0
	v_mov_b64_e32 v[102:103], 0
	v_mov_b64_e32 v[104:105], 0
	v_mov_b64_e32 v[106:107], 0
	v_mov_b64_e32 v[108:109], 0
	v_mov_b64_e32 v[110:111], 0
	v_mov_b64_e32 v[112:113], 0
	v_mov_b64_e32 v[114:115], 0
	v_mov_b64_e32 v[116:117], 0
	v_mov_b64_e32 v[118:119], 0
	v_mov_b64_e32 v[120:121], 0
	v_mov_b64_e32 v[122:123], 0
	v_mov_b64_e32 v[124:125], 0
	v_mov_b64_e32 v[126:127], 0
	s_addc_u32 s47, s21, 0
	s_mov_b32 s48, -2
	s_waitcnt lgkmcnt(0)
